# local barrier polls without s_sleep
# speedup vs baseline: 1.0509x; 1.0027x over previous
.Lmy_lpoll_d:
	global_load_dword v0, v65, s[8:9] sc1
	s_waitcnt vmcnt(0)
	v_cmp_lt_u32_e32 vcc, v0, v2
	s_cbranch_vccz .LBB0_828
	s_nop 0
	s_add_i32 s21, s21, 1
	s_cmp_lt_u32 s21, 0x100000
	s_cbranch_scc1 .Lmy_lpoll_d
	s_branch .LBB0_828

.Lmy_lpoll_a:
	global_load_dword v0, v65, s[20:21] sc1
	s_waitcnt vmcnt(0)
	v_cmp_lt_u32_e32 vcc, v0, v2
	s_cbranch_vccz .LBB0_2096
	s_nop 0
	s_add_i32 s5, s5, 1
	s_cmp_lt_u32 s5, 0x100000
	s_cbranch_scc1 .Lmy_lpoll_a
	s_branch .LBB0_2096

.Lmy_lpoll_b:
	global_load_dword v0, v65, s[22:23] sc1
	s_waitcnt vmcnt(0)
	v_cmp_lt_u32_e32 vcc, v0, v2
	s_cbranch_vccz .LBB0_2149
	s_nop 0
	s_add_i32 s5, s5, 1
	s_cmp_lt_u32 s5, 0x100000
	s_cbranch_scc1 .Lmy_lpoll_b
	s_branch .LBB0_2149
